# phase-0 silu(c) table fill loop unrolled x4 (4 loads in flight) on top of FFN-out row-split
# speedup vs baseline: 1.0128x; 1.0039x over previous
; __global__ void __launch_bounds__(512, 2) fwd_kernel(Params P) {
;     ...
;         for (int un = c; un < 288; un += G) {
;             __syncthreads();
;             for (int i = tid; i < 24 * 1024; i += 512) { const int b = i >> 10, k = i & 1023; const float v = b < 16 ? P.in[8][b * 1024 + k] : P.in[9][(b - 16) * 1024 + k];
;                 sc[k * 24 + b] = v / (1.0f + __expf(-v)); }
;             __syncthreads();
;             const int l = un / 144, n0 = (un % 144) * 64, col = n0 + lane;
;             const float* Wp = P.in[10] + (size_t)l * 1024 * 9216 + col;
;             float acc[24];
; #pragma unroll
;             for (int b = 0; b < 24; ++b) acc[b] = 0.f;
.LBB0_138:
	v_and_b32_e32 v3, 0x7fff, v2
	v_add_u32_e32 v3, 0xffffc000, v3
	v_cmp_gt_u32_e32 vcc, 0x4000, v2
	s_nop 1
	v_cndmask_b32_e32 v42, v3, v2, vcc
	v_cndmask_b32_e32 v5, v103, v104, vcc
	v_cndmask_b32_e32 v4, v105, v106, vcc
	v_lshl_add_u64 v[4:5], v[42:43], 2, v[4:5]
	global_load_dword v24, v[4:5], off
	v_and_b32_e32 v4, 0x3ff, v2
	v_lshrrev_b32_e32 v5, 8, v2
	v_mul_u32_u24_e32 v4, 0x60, v4
	v_and_b32_e32 v5, 0xfffffc, v5
	v_add3_u32 v28, 0, v4, v5
	v_add_u32_e32 v6, 0x200, v2
	v_and_b32_e32 v3, 0x7fff, v6
	v_add_u32_e32 v3, 0xffffc000, v3
	v_cmp_gt_u32_e32 vcc, 0x4000, v6
	s_nop 1
	v_cndmask_b32_e32 v42, v3, v6, vcc
	v_cndmask_b32_e32 v5, v103, v104, vcc
	v_cndmask_b32_e32 v4, v105, v106, vcc
	v_lshl_add_u64 v[4:5], v[42:43], 2, v[4:5]
	global_load_dword v25, v[4:5], off
	v_and_b32_e32 v4, 0x3ff, v6
	v_lshrrev_b32_e32 v5, 8, v6
	v_mul_u32_u24_e32 v4, 0x60, v4
	v_and_b32_e32 v5, 0xfffffc, v5
	v_add3_u32 v29, 0, v4, v5
	v_add_u32_e32 v6, 0x400, v2
	v_and_b32_e32 v3, 0x7fff, v6
	v_add_u32_e32 v3, 0xffffc000, v3
	v_cmp_gt_u32_e32 vcc, 0x4000, v6
	s_nop 1
	v_cndmask_b32_e32 v42, v3, v6, vcc
	v_cndmask_b32_e32 v5, v103, v104, vcc
	v_cndmask_b32_e32 v4, v105, v106, vcc
	v_lshl_add_u64 v[4:5], v[42:43], 2, v[4:5]
	global_load_dword v26, v[4:5], off
	v_and_b32_e32 v4, 0x3ff, v6
	v_lshrrev_b32_e32 v5, 8, v6
	v_mul_u32_u24_e32 v4, 0x60, v4
	v_and_b32_e32 v5, 0xfffffc, v5
	v_add3_u32 v30, 0, v4, v5
	v_add_u32_e32 v6, 0x600, v2
	v_and_b32_e32 v3, 0x7fff, v6
	v_add_u32_e32 v3, 0xffffc000, v3
	v_cmp_gt_u32_e32 vcc, 0x4000, v6
	s_nop 1
	v_cndmask_b32_e32 v42, v3, v6, vcc
	v_cndmask_b32_e32 v5, v103, v104, vcc
	v_cndmask_b32_e32 v4, v105, v106, vcc
	v_lshl_add_u64 v[4:5], v[42:43], 2, v[4:5]
	global_load_dword v27, v[4:5], off
	v_and_b32_e32 v4, 0x3ff, v6
	v_lshrrev_b32_e32 v5, 8, v6
	v_mul_u32_u24_e32 v4, 0x60, v4
	v_and_b32_e32 v5, 0xfffffc, v5
	v_add3_u32 v31, 0, v4, v5
	v_cmp_lt_u32_e32 vcc, 0x57ff, v2
	s_or_b64 s[12:13], vcc, s[12:13]
	v_add_u32_e32 v2, 0x800, v2
	s_waitcnt vmcnt(0)
	v_mul_f32_e32 v5, 0xbfb8aa3b, v24
	v_exp_f32_e32 v5, v5
	s_nop 0
	v_add_f32_e32 v5, 1.0, v5
	v_div_scale_f32 v6, s[16:17], v5, v5, v24
	v_rcp_f32_e32 v7, v6
	v_div_scale_f32 v8, vcc, v24, v5, v24
	v_fma_f32 v9, -v6, v7, 1.0
	v_fmac_f32_e32 v7, v9, v7
	v_mul_f32_e32 v9, v8, v7
	v_fma_f32 v10, -v6, v9, v8
	v_fmac_f32_e32 v9, v10, v7
	v_fma_f32 v6, -v6, v9, v8
	v_div_fmas_f32 v6, v6, v7, v9
	v_div_fixup_f32 v6, v6, v5, v24
	ds_write_b32 v28, v6
	v_mul_f32_e32 v5, 0xbfb8aa3b, v25
	v_exp_f32_e32 v5, v5
	s_nop 0
	v_add_f32_e32 v5, 1.0, v5
	v_div_scale_f32 v6, s[16:17], v5, v5, v25
	v_rcp_f32_e32 v7, v6
	v_div_scale_f32 v8, vcc, v25, v5, v25
	v_fma_f32 v9, -v6, v7, 1.0
	v_fmac_f32_e32 v7, v9, v7
	v_mul_f32_e32 v9, v8, v7
	v_fma_f32 v10, -v6, v9, v8
	v_fmac_f32_e32 v9, v10, v7
	v_fma_f32 v6, -v6, v9, v8
	v_div_fmas_f32 v6, v6, v7, v9
	v_div_fixup_f32 v6, v6, v5, v25
	ds_write_b32 v29, v6
	v_mul_f32_e32 v5, 0xbfb8aa3b, v26
	v_exp_f32_e32 v5, v5
	s_nop 0
	v_add_f32_e32 v5, 1.0, v5
	v_div_scale_f32 v6, s[16:17], v5, v5, v26
	v_rcp_f32_e32 v7, v6
	v_div_scale_f32 v8, vcc, v26, v5, v26
	v_fma_f32 v9, -v6, v7, 1.0
	v_fmac_f32_e32 v7, v9, v7
	v_mul_f32_e32 v9, v8, v7
	v_fma_f32 v10, -v6, v9, v8
	v_fmac_f32_e32 v9, v10, v7
	v_fma_f32 v6, -v6, v9, v8
	v_div_fmas_f32 v6, v6, v7, v9
	v_div_fixup_f32 v6, v6, v5, v26
	ds_write_b32 v30, v6
	v_mul_f32_e32 v5, 0xbfb8aa3b, v27
	v_exp_f32_e32 v5, v5
	s_nop 0
	v_add_f32_e32 v5, 1.0, v5
	v_div_scale_f32 v6, s[16:17], v5, v5, v27
	v_rcp_f32_e32 v7, v6
	v_div_scale_f32 v8, vcc, v27, v5, v27
	v_fma_f32 v9, -v6, v7, 1.0
	v_fmac_f32_e32 v7, v9, v7
	v_mul_f32_e32 v9, v8, v7
	v_fma_f32 v10, -v6, v9, v8
	v_fmac_f32_e32 v9, v10, v7
	v_fma_f32 v6, -v6, v9, v8
	v_div_fmas_f32 v6, v6, v7, v9
	v_div_fixup_f32 v6, v6, v5, v27
	ds_write_b32 v31, v6
	s_andn2_b64 exec, exec, s[12:13]
	s_cbranch_execnz .LBB0_138
	s_or_b64 exec, exec, s[12:13]
	s_mul_hi_i32 s12, s44, 0x38e38e39
	s_lshr_b32 s13, s12, 31
	s_ashr_i32 s18, s12, 5
	s_add_i32 s18, s18, s13
	s_mul_hi_i32 s23, s18, 0x2400000
	s_mul_i32 s45, s18, 0x2400000
	s_and_b64 vcc, exec, s[4:5]
	v_lshl_or_b32 v22, s44, 6, v238
	s_waitcnt lgkmcnt(0)
	s_barrier
	s_cbranch_vccnz .LBB0_143
	s_mul_i32 s12, s18, 0x2400
	v_subrev_u32_e32 v2, s12, v22
	s_add_u32 s12, s41, s45
	v_ashrrev_i32_e32 v3, 31, v2
	s_addc_u32 s13, s42, s23
	v_mov_b32_e32 v62, 0
	v_lshl_add_u64 v[2:3], v[2:3], 2, s[12:13]
	s_mov_b32 s12, s43
	s_mov_b32 s13, s40
	v_mov_b32_e32 v63, v62
	v_mov_b32_e32 v70, v62
	v_mov_b32_e32 v71, v62
	v_mov_b32_e32 v68, v62
	v_mov_b32_e32 v69, v62
	v_mov_b32_e32 v66, v62
	v_mov_b32_e32 v67, v62
	v_mov_b32_e32 v64, v62
	v_mov_b32_e32 v65, v62
	v_mov_b32_e32 v60, v62
	v_mov_b32_e32 v61, v62
	v_mov_b32_e32 v58, v62
	v_mov_b32_e32 v59, v62
	v_mov_b32_e32 v56, v62
	v_mov_b32_e32 v57, v62
	v_mov_b32_e32 v54, v62
	v_mov_b32_e32 v55, v62
	v_mov_b32_e32 v52, v62
	v_mov_b32_e32 v53, v62
	v_mov_b32_e32 v50, v62
	v_mov_b32_e32 v51, v62
	v_mov_b32_e32 v48, v62
	v_mov_b32_e32 v49, v62
